# ssm1 scan too: input projection on v_mfma_f32_32x32x2_f32 (exact f32), recurrence on VALU unchanged
# speedup vs baseline: 1.0394x; 1.0058x over previous
; DI int tidx() { int t = threadIdx.x & 255; asm volatile("" : "+v"(t)); return t; }
; DI void ssm_stage_u(PREF p, int b, int c, int gq, float* uS) {
;   const int tid = tidx();
;   int row = tid >> 2, cc = (tid & 3) * 16;
;   const u16* src = p.hb + (size_t)(b * S_ + c * 64 + row) * HW + OFF_U + gq * 64 + cc;
;   float f[16];
;   unpack8(*(const u32x4*)src, f); unpack8(*(const u32x4*)(src + 8), f + 8);
; #pragma unroll
;   for (int j = 0; j < 4; ++j) *(float4*)(uS + row * 64 + cc + 4 * j) = make_float4(f[4 * j], f[4 * j + 1], f[4 * j + 2], f[4 * j + 3]);
; }
; DI void ssm1_item(PREF p, int l, int item, unsigned char* ldsb) {
;   const int gq = item & 3, c = (item >> 2) & 63, b = item >> 8;
;   const int tid = tidx(), w = tid >> 6, lane = tid & 63;
;   const int g = gq * 4 + w;
;   float* uS = (float*)ldsb;
;   __syncthreads();
;   ssm_stage_u(p, b, c, gq, uS);
;   __syncthreads();
;   const size_t pi = (size_t)(l * 16 + g) * 64 + lane;
;   float bre[16], bim[16];
; #pragma unroll
;   for (int j = 0; j < 16; ++j) { bre[j] = p.bbre[pi * 16 + j]; bim[j] = p.bbim[pi * 16 + j]; }
;   const float lr = p.lam[pi * 2], li = p.lam[pi * 2 + 1];
;   float hr = 0.f, hi = 0.f;
;   for (int t = 0; t < 64; ++t) SSM_STEP(t)
.LBB0_422:
	s_ashr_i32 s14, s12, 8
	v_mov_b32_e32 v25, v169
	v_mov_b32_e32 v0, v169
	s_lshl_b32 s1, s12, 4
	s_waitcnt lgkmcnt(0)
	s_barrier
	s_lshl_b32 s0, s14, 12
	s_and_b32 s15, s1, 0xfc0
	v_ashrrev_i32_e32 v10, 2, v0
	v_lshlrev_b32_e32 v0, 4, v0
	s_or_b32 s0, s15, s0
	v_and_b32_e32 v11, 48, v0
	v_add_u32_e32 v0, s0, v10
	s_load_dwordx2 s[0:1], s[18:19], 0x140
	s_and_b32 s16, s12, 3
	s_lshl_b32 s52, s16, 7
	v_ashrrev_i32_e32 v12, 6, v25
	v_lshl_add_u32 v41, s16, 2, v12
	s_waitcnt lgkmcnt(0)
	v_mov_b64_e32 v[2:3], s[0:1]
	v_mad_i64_i32 v[2:3], s[0:1], v0, s60, v[2:3]
	v_lshl_add_u64 v[2:3], v[2:3], 0, s[52:53]
	v_lshlrev_b32_e32 v0, 1, v11
	v_lshl_add_u64 v[6:7], v[2:3], 0, v[0:1]
	global_load_dwordx4 v[2:5], v[6:7], off offset:2880
	s_nop 0
	global_load_dwordx4 v[6:9], v[6:7], off offset:2896
	v_lshlrev_b32_e32 v12, 8, v10
	v_lshlrev_b32_e32 v11, 2, v11
	v_add_u32_e32 v10, s13, v41
	s_load_dwordx2 s[0:1], s[18:19], 0x118
	v_add3_u32 v24, s33, v12, v11
	v_ashrrev_i32_e32 v11, 31, v10
	v_and_b32_e32 v0, 63, v25
	v_lshlrev_b64 v[22:23], 6, v[10:11]
	v_or_b32_e32 v22, v22, v0
	v_lshlrev_b64 v[10:11], 6, v[22:23]
	v_lshl_add_u64 v[18:19], s[10:11], 0, v[10:11]
	s_waitcnt lgkmcnt(0)
	v_lshl_add_u64 v[20:21], s[0:1], 0, v[10:11]
	v_lshl_add_u64 v[22:23], v[22:23], 3, s[8:9]
	v_and_b32_e32 v25, 0xffffffc0, v25
	s_mov_b32 s16, 0
	v_add_u32_e32 v42, s33, v25
	v_mov_b32_e32 v40, 0
	s_waitcnt vmcnt(1)
	v_lshlrev_b32_e32 v10, 16, v2
	v_and_b32_e32 v11, 0xffff0000, v2
	v_lshlrev_b32_e32 v12, 16, v3
	v_and_b32_e32 v13, 0xffff0000, v3
	v_lshlrev_b32_e32 v2, 16, v4
	v_and_b32_e32 v3, 0xffff0000, v4
	v_lshlrev_b32_e32 v4, 16, v5
	v_and_b32_e32 v5, 0xffff0000, v5
	s_waitcnt vmcnt(0)
	v_lshlrev_b32_e32 v14, 16, v6
	v_and_b32_e32 v15, 0xffff0000, v6
	v_lshlrev_b32_e32 v16, 16, v7
	v_and_b32_e32 v17, 0xffff0000, v7
	v_lshlrev_b32_e32 v6, 16, v8
	v_and_b32_e32 v7, 0xffff0000, v8
	v_lshlrev_b32_e32 v8, 16, v9
	v_and_b32_e32 v9, 0xffff0000, v9
	ds_write_b128 v24, v[10:13]
	ds_write_b128 v24, v[2:5] offset:16
	ds_write_b128 v24, v[14:17] offset:32
	ds_write_b128 v24, v[6:9] offset:48
	s_waitcnt lgkmcnt(0)
	s_barrier
	global_load_dwordx4 v[2:5], v[18:19], off offset:16
	global_load_dwordx4 v[6:9], v[20:21], off offset:16
	global_load_dwordx4 v[30:33], v[18:19], off offset:32
	global_load_dwordx4 v[10:13], v[20:21], off offset:32
	global_load_dwordx4 v[34:37], v[18:19], off offset:48
	global_load_dwordx4 v[14:17], v[20:21], off offset:48
	global_load_dwordx4 v[44:47], v[18:19], off
	s_nop 0
	global_load_dwordx4 v[18:21], v[20:21], off
	v_mov_b32_e32 v24, 0
	global_load_dwordx2 v[22:23], v[22:23], off
	s_waitcnt vmcnt(8)
	v_mov_b32_e32 v26, v5
	s_waitcnt vmcnt(7)
	v_mov_b32_e32 v27, v9
	s_waitcnt vmcnt(6)
	v_mov_b32_e32 v28, v30
	s_waitcnt vmcnt(5)
	v_mov_b32_e32 v29, v10
	v_mov_b32_e32 v10, v31
	v_mov_b32_e32 v30, v32
	v_mov_b32_e32 v31, v12
	v_mov_b32_e32 v12, v33
	s_waitcnt vmcnt(4)
	v_mov_b32_e32 v32, v34
	s_waitcnt vmcnt(3)
	v_mov_b32_e32 v33, v14
	v_mov_b32_e32 v14, v35
	v_mov_b32_e32 v34, v36
	v_mov_b32_e32 v35, v16
	v_mov_b32_e32 v16, v37
	v_mov_b32_e32 v5, v8
	s_waitcnt vmcnt(2)
	v_mov_b32_e32 v8, v44
	s_waitcnt vmcnt(1)
	v_mov_b32_e32 v9, v18
	v_mov_b32_e32 v18, v45
	v_mov_b32_e32 v36, v46
	v_mov_b32_e32 v37, v20
	v_mov_b32_e32 v20, v47
	v_mov_b32_e32 v38, v2
	v_mov_b32_e32 v39, v6
	v_mov_b32_e32 v6, v3
	s_waitcnt vmcnt(0)
	v_pk_mov_b32 v[2:3], v[22:23], v[22:23] op_sel:[1,0]
	v_mov_b32_e32 v25, 0
	v_permlane32_swap_b32 v8, v18
	v_permlane32_swap_b32 v9, v19
	v_permlane32_swap_b32 v36, v20
	v_permlane32_swap_b32 v37, v21
	v_permlane32_swap_b32 v38, v6
	v_permlane32_swap_b32 v39, v7
	v_permlane32_swap_b32 v4, v26
	v_permlane32_swap_b32 v5, v27
	v_permlane32_swap_b32 v28, v10
	v_permlane32_swap_b32 v29, v11
	v_permlane32_swap_b32 v30, v12
	v_permlane32_swap_b32 v31, v13
	v_permlane32_swap_b32 v32, v14
	v_permlane32_swap_b32 v33, v15
	v_permlane32_swap_b32 v34, v16
	v_permlane32_swap_b32 v35, v17
	v_bfe_u32 v128, v172, 2, 1
	v_bfe_u32 v129, v172, 3, 2
	v_and_b32_e32 v130, 3, v172
	v_lshlrev_b32_e32 v128, 4, v128
	v_lshl_add_u32 v128, v129, 2, v128
	v_add_u32_e32 v128, v128, v130
	v_lshlrev_b32_e32 v128, 8, v128
	v_lshrrev_b32_e32 v129, 5, v172
	v_lshl_add_u32 v126, v129, 2, v128
	v_add_u32_e32 v127, v42, v126
	ds_read2_b32 v[118:119], v127 offset0:0 offset1:2
	ds_read2_b32 v[120:121], v127 offset0:4 offset1:6
	ds_read2_b32 v[122:123], v127 offset0:8 offset1:10
	ds_read2_b32 v[124:125], v127 offset0:12 offset1:14
	s_waitcnt lgkmcnt(0)
; DI void ssm1_item(PREF p, int l, int item, unsigned char* ldsb) {
;     ...
;   for (int t = 0; t < 64; ++t) SSM_STEP(t)
	v_mfma_f32_32x32x2_f32 v[184:199], v118, v8, 0
	v_mfma_f32_32x32x2_f32 v[200:215], v118, v9, 0
	v_mfma_f32_32x32x2_f32 v[216:231], v118, v18, 0
	v_mfma_f32_32x32x2_f32 v[232:247], v118, v19, 0
	v_mfma_f32_32x32x2_f32 v[184:199], v119, v36, v[184:199]
	v_mfma_f32_32x32x2_f32 v[200:215], v119, v37, v[200:215]
	v_mfma_f32_32x32x2_f32 v[216:231], v119, v20, v[216:231]
	v_mfma_f32_32x32x2_f32 v[232:247], v119, v21, v[232:247]
	v_mfma_f32_32x32x2_f32 v[184:199], v120, v38, v[184:199]
	v_mfma_f32_32x32x2_f32 v[200:215], v120, v39, v[200:215]
	v_mfma_f32_32x32x2_f32 v[216:231], v120, v6, v[216:231]
	v_mfma_f32_32x32x2_f32 v[232:247], v120, v7, v[232:247]
	v_mfma_f32_32x32x2_f32 v[184:199], v121, v4, v[184:199]
	v_mfma_f32_32x32x2_f32 v[200:215], v121, v5, v[200:215]
	v_mfma_f32_32x32x2_f32 v[216:231], v121, v26, v[216:231]
	v_mfma_f32_32x32x2_f32 v[232:247], v121, v27, v[232:247]
	v_mfma_f32_32x32x2_f32 v[184:199], v122, v28, v[184:199]
	v_mfma_f32_32x32x2_f32 v[200:215], v122, v29, v[200:215]
	v_mfma_f32_32x32x2_f32 v[216:231], v122, v10, v[216:231]
	v_mfma_f32_32x32x2_f32 v[232:247], v122, v11, v[232:247]
	v_mfma_f32_32x32x2_f32 v[184:199], v123, v30, v[184:199]
	v_mfma_f32_32x32x2_f32 v[200:215], v123, v31, v[200:215]
	v_mfma_f32_32x32x2_f32 v[216:231], v123, v12, v[216:231]
	v_mfma_f32_32x32x2_f32 v[232:247], v123, v13, v[232:247]
	v_mfma_f32_32x32x2_f32 v[184:199], v124, v32, v[184:199]
	v_mfma_f32_32x32x2_f32 v[200:215], v124, v33, v[200:215]
	v_mfma_f32_32x32x2_f32 v[216:231], v124, v14, v[216:231]
	v_mfma_f32_32x32x2_f32 v[232:247], v124, v15, v[232:247]
	v_mfma_f32_32x32x2_f32 v[184:199], v125, v34, v[184:199]
	v_mfma_f32_32x32x2_f32 v[200:215], v125, v35, v[200:215]
	v_mfma_f32_32x32x2_f32 v[216:231], v125, v16, v[216:231]
	v_mfma_f32_32x32x2_f32 v[232:247], v125, v17, v[232:247]
	s_nop 18
	v_permlane32_swap_b32 v184, v216
	s_nop 18
	v_permlane32_swap_b32 v200, v232
	s_nop 16
	v_permlane32_swap_b32 v185, v217
	s_nop 16
	v_permlane32_swap_b32 v201, v233
	s_nop 14
	v_permlane32_swap_b32 v186, v218
	s_nop 14
	v_permlane32_swap_b32 v202, v234
	s_nop 12
	v_permlane32_swap_b32 v187, v219
	s_nop 12
	v_permlane32_swap_b32 v203, v235
	s_nop 10
	v_permlane32_swap_b32 v188, v220
	s_nop 10
	v_permlane32_swap_b32 v204, v236
	s_nop 8
	v_permlane32_swap_b32 v189, v221
	s_nop 8
	v_permlane32_swap_b32 v205, v237
	s_nop 6
	v_permlane32_swap_b32 v190, v222
	s_nop 6
	v_permlane32_swap_b32 v206, v238
	s_nop 4
	v_permlane32_swap_b32 v191, v223
	s_nop 4
	v_permlane32_swap_b32 v207, v239
	s_nop 2
	v_permlane32_swap_b32 v192, v224
	s_nop 2
	v_permlane32_swap_b32 v208, v240
	s_nop 0
	v_permlane32_swap_b32 v193, v225
	s_nop 0
	v_permlane32_swap_b32 v209, v241
	v_permlane32_swap_b32 v194, v226
	v_permlane32_swap_b32 v210, v242
	v_permlane32_swap_b32 v195, v227
	v_permlane32_swap_b32 v211, v243
	v_permlane32_swap_b32 v196, v228
	v_permlane32_swap_b32 v212, v244
	v_permlane32_swap_b32 v197, v229
	v_permlane32_swap_b32 v213, v245
	v_permlane32_swap_b32 v198, v230
	v_permlane32_swap_b32 v214, v246
	v_permlane32_swap_b32 v199, v231
	v_permlane32_swap_b32 v215, v247
	v_mul_f32_e32 v128, v23, v25
	v_mul_f32_e32 v129, v22, v25
	v_fma_f32 v130, v22, v24, -v128
	v_fma_f32 v131, v23, v24, v129
	v_add_f32_e32 v24, v130, v184
	v_add_f32_e32 v25, v131, v200
	v_mul_f32_e32 v128, v23, v25
	v_mul_f32_e32 v129, v22, v25
	v_fma_f32 v130, v22, v24, -v128
	v_fma_f32 v131, v23, v24, v129
	v_add_f32_e32 v24, v130, v185
	v_add_f32_e32 v25, v131, v201
	v_mul_f32_e32 v128, v23, v25
	v_mul_f32_e32 v129, v22, v25
	v_fma_f32 v130, v22, v24, -v128
	v_fma_f32 v131, v23, v24, v129
	v_add_f32_e32 v24, v130, v186
	v_add_f32_e32 v25, v131, v202
	v_mul_f32_e32 v128, v23, v25
	v_mul_f32_e32 v129, v22, v25
	v_fma_f32 v130, v22, v24, -v128
	v_fma_f32 v131, v23, v24, v129
	v_add_f32_e32 v24, v130, v187
	v_add_f32_e32 v25, v131, v203
	v_mul_f32_e32 v128, v23, v25
	v_mul_f32_e32 v129, v22, v25
	v_fma_f32 v130, v22, v24, -v128
	v_fma_f32 v131, v23, v24, v129
	v_add_f32_e32 v24, v130, v188
	v_add_f32_e32 v25, v131, v204
	v_mul_f32_e32 v128, v23, v25
	v_mul_f32_e32 v129, v22, v25
	v_fma_f32 v130, v22, v24, -v128
	v_fma_f32 v131, v23, v24, v129
	v_add_f32_e32 v24, v130, v189
	v_add_f32_e32 v25, v131, v205
	v_mul_f32_e32 v128, v23, v25
	v_mul_f32_e32 v129, v22, v25
	v_fma_f32 v130, v22, v24, -v128
	v_fma_f32 v131, v23, v24, v129
	v_add_f32_e32 v24, v130, v190
	v_add_f32_e32 v25, v131, v206
	v_mul_f32_e32 v128, v23, v25
	v_mul_f32_e32 v129, v22, v25
	v_fma_f32 v130, v22, v24, -v128
	v_fma_f32 v131, v23, v24, v129
	v_add_f32_e32 v24, v130, v191
	v_add_f32_e32 v25, v131, v207
	v_mul_f32_e32 v128, v23, v25
	v_mul_f32_e32 v129, v22, v25
	v_fma_f32 v130, v22, v24, -v128
	v_fma_f32 v131, v23, v24, v129
	v_add_f32_e32 v24, v130, v192
	v_add_f32_e32 v25, v131, v208
	v_mul_f32_e32 v128, v23, v25
	v_mul_f32_e32 v129, v22, v25
	v_fma_f32 v130, v22, v24, -v128
	v_fma_f32 v131, v23, v24, v129
	v_add_f32_e32 v24, v130, v193
	v_add_f32_e32 v25, v131, v209
	v_mul_f32_e32 v128, v23, v25
	v_mul_f32_e32 v129, v22, v25
	v_fma_f32 v130, v22, v24, -v128
	v_fma_f32 v131, v23, v24, v129
	v_add_f32_e32 v24, v130, v194
	v_add_f32_e32 v25, v131, v210
	v_mul_f32_e32 v128, v23, v25
	v_mul_f32_e32 v129, v22, v25
	v_fma_f32 v130, v22, v24, -v128
	v_fma_f32 v131, v23, v24, v129
	v_add_f32_e32 v24, v130, v195
	v_add_f32_e32 v25, v131, v211
	v_mul_f32_e32 v128, v23, v25
	v_mul_f32_e32 v129, v22, v25
	v_fma_f32 v130, v22, v24, -v128
	v_fma_f32 v131, v23, v24, v129
	v_add_f32_e32 v24, v130, v196
	v_add_f32_e32 v25, v131, v212
	v_mul_f32_e32 v128, v23, v25
	v_mul_f32_e32 v129, v22, v25
	v_fma_f32 v130, v22, v24, -v128
	v_fma_f32 v131, v23, v24, v129
; DI void ssm1_item(PREF p, int l, int item, unsigned char* ldsb) {
;     ...
;   for (int t = 0; t < 64; ++t) SSM_STEP(t)
	v_add_f32_e32 v24, v130, v197
	v_add_f32_e32 v25, v131, v213
	v_mul_f32_e32 v128, v23, v25
	v_mul_f32_e32 v129, v22, v25
	v_fma_f32 v130, v22, v24, -v128
	v_fma_f32 v131, v23, v24, v129
	v_add_f32_e32 v24, v130, v198
	v_add_f32_e32 v25, v131, v214
	v_mul_f32_e32 v128, v23, v25
	v_mul_f32_e32 v129, v22, v25
	v_fma_f32 v130, v22, v24, -v128
	v_fma_f32 v131, v23, v24, v129
	v_add_f32_e32 v24, v130, v199
	v_add_f32_e32 v25, v131, v215
	v_mul_f32_e32 v128, v23, v25
	v_mul_f32_e32 v129, v22, v25
	v_fma_f32 v130, v22, v24, -v128
	v_fma_f32 v131, v23, v24, v129
	v_add_f32_e32 v24, v130, v216
	v_add_f32_e32 v25, v131, v232
	v_mul_f32_e32 v128, v23, v25
	v_mul_f32_e32 v129, v22, v25
	v_fma_f32 v130, v22, v24, -v128
	v_fma_f32 v131, v23, v24, v129
	v_add_f32_e32 v24, v130, v217
	v_add_f32_e32 v25, v131, v233
	v_mul_f32_e32 v128, v23, v25
	v_mul_f32_e32 v129, v22, v25
	v_fma_f32 v130, v22, v24, -v128
	v_fma_f32 v131, v23, v24, v129
	v_add_f32_e32 v24, v130, v218
	v_add_f32_e32 v25, v131, v234
	v_mul_f32_e32 v128, v23, v25
	v_mul_f32_e32 v129, v22, v25
	v_fma_f32 v130, v22, v24, -v128
	v_fma_f32 v131, v23, v24, v129
	v_add_f32_e32 v24, v130, v219
	v_add_f32_e32 v25, v131, v235
	v_mul_f32_e32 v128, v23, v25
	v_mul_f32_e32 v129, v22, v25
	v_fma_f32 v130, v22, v24, -v128
	v_fma_f32 v131, v23, v24, v129
	v_add_f32_e32 v24, v130, v220
	v_add_f32_e32 v25, v131, v236
	v_mul_f32_e32 v128, v23, v25
	v_mul_f32_e32 v129, v22, v25
	v_fma_f32 v130, v22, v24, -v128
	v_fma_f32 v131, v23, v24, v129
	v_add_f32_e32 v24, v130, v221
	v_add_f32_e32 v25, v131, v237
	v_mul_f32_e32 v128, v23, v25
	v_mul_f32_e32 v129, v22, v25
	v_fma_f32 v130, v22, v24, -v128
	v_fma_f32 v131, v23, v24, v129
	v_add_f32_e32 v24, v130, v222
	v_add_f32_e32 v25, v131, v238
	v_mul_f32_e32 v128, v23, v25
	v_mul_f32_e32 v129, v22, v25
	v_fma_f32 v130, v22, v24, -v128
	v_fma_f32 v131, v23, v24, v129
	v_add_f32_e32 v24, v130, v223
	v_add_f32_e32 v25, v131, v239
	v_mul_f32_e32 v128, v23, v25
	v_mul_f32_e32 v129, v22, v25
	v_fma_f32 v130, v22, v24, -v128
	v_fma_f32 v131, v23, v24, v129
	v_add_f32_e32 v24, v130, v224
	v_add_f32_e32 v25, v131, v240
	v_mul_f32_e32 v128, v23, v25
	v_mul_f32_e32 v129, v22, v25
	v_fma_f32 v130, v22, v24, -v128
	v_fma_f32 v131, v23, v24, v129
	v_add_f32_e32 v24, v130, v225
	v_add_f32_e32 v25, v131, v241
	v_mul_f32_e32 v128, v23, v25
	v_mul_f32_e32 v129, v22, v25
	v_fma_f32 v130, v22, v24, -v128
	v_fma_f32 v131, v23, v24, v129
	v_add_f32_e32 v24, v130, v226
	v_add_f32_e32 v25, v131, v242
	v_mul_f32_e32 v128, v23, v25
	v_mul_f32_e32 v129, v22, v25
	v_fma_f32 v130, v22, v24, -v128
	v_fma_f32 v131, v23, v24, v129
	v_add_f32_e32 v24, v130, v227
	v_add_f32_e32 v25, v131, v243
	v_mul_f32_e32 v128, v23, v25
	v_mul_f32_e32 v129, v22, v25
	v_fma_f32 v130, v22, v24, -v128
	v_fma_f32 v131, v23, v24, v129
	v_add_f32_e32 v24, v130, v228
	v_add_f32_e32 v25, v131, v244
	v_mul_f32_e32 v128, v23, v25
	v_mul_f32_e32 v129, v22, v25
	v_fma_f32 v130, v22, v24, -v128
	v_fma_f32 v131, v23, v24, v129
	v_add_f32_e32 v24, v130, v229
	v_add_f32_e32 v25, v131, v245
	v_mul_f32_e32 v128, v23, v25
	v_mul_f32_e32 v129, v22, v25
	v_fma_f32 v130, v22, v24, -v128
	v_fma_f32 v131, v23, v24, v129
	v_add_f32_e32 v24, v130, v230
	v_add_f32_e32 v25, v131, v246
	v_mul_f32_e32 v128, v23, v25
	v_mul_f32_e32 v129, v22, v25
	v_fma_f32 v130, v22, v24, -v128
	v_fma_f32 v131, v23, v24, v129
	v_add_f32_e32 v24, v130, v231
	v_add_f32_e32 v25, v131, v247
	v_add_u32_e32 v127, 0x2000, v127
	ds_read2_b32 v[118:119], v127 offset0:0 offset1:2
	ds_read2_b32 v[120:121], v127 offset0:4 offset1:6
	ds_read2_b32 v[122:123], v127 offset0:8 offset1:10
	ds_read2_b32 v[124:125], v127 offset0:12 offset1:14
	s_waitcnt lgkmcnt(0)
	v_mfma_f32_32x32x2_f32 v[184:199], v118, v8, 0
	v_mfma_f32_32x32x2_f32 v[200:215], v118, v9, 0
	v_mfma_f32_32x32x2_f32 v[216:231], v118, v18, 0
	v_mfma_f32_32x32x2_f32 v[232:247], v118, v19, 0
	v_mfma_f32_32x32x2_f32 v[184:199], v119, v36, v[184:199]
	v_mfma_f32_32x32x2_f32 v[200:215], v119, v37, v[200:215]
	v_mfma_f32_32x32x2_f32 v[216:231], v119, v20, v[216:231]
	v_mfma_f32_32x32x2_f32 v[232:247], v119, v21, v[232:247]
	v_mfma_f32_32x32x2_f32 v[184:199], v120, v38, v[184:199]
	v_mfma_f32_32x32x2_f32 v[200:215], v120, v39, v[200:215]
	v_mfma_f32_32x32x2_f32 v[216:231], v120, v6, v[216:231]
	v_mfma_f32_32x32x2_f32 v[232:247], v120, v7, v[232:247]
	v_mfma_f32_32x32x2_f32 v[184:199], v121, v4, v[184:199]
	v_mfma_f32_32x32x2_f32 v[200:215], v121, v5, v[200:215]
	v_mfma_f32_32x32x2_f32 v[216:231], v121, v26, v[216:231]
	v_mfma_f32_32x32x2_f32 v[232:247], v121, v27, v[232:247]
	v_mfma_f32_32x32x2_f32 v[184:199], v122, v28, v[184:199]
	v_mfma_f32_32x32x2_f32 v[200:215], v122, v29, v[200:215]
	v_mfma_f32_32x32x2_f32 v[216:231], v122, v10, v[216:231]
	v_mfma_f32_32x32x2_f32 v[232:247], v122, v11, v[232:247]
	v_mfma_f32_32x32x2_f32 v[184:199], v123, v30, v[184:199]
	v_mfma_f32_32x32x2_f32 v[200:215], v123, v31, v[200:215]
	v_mfma_f32_32x32x2_f32 v[216:231], v123, v12, v[216:231]
	v_mfma_f32_32x32x2_f32 v[232:247], v123, v13, v[232:247]
	v_mfma_f32_32x32x2_f32 v[184:199], v124, v32, v[184:199]
	v_mfma_f32_32x32x2_f32 v[200:215], v124, v33, v[200:215]
	v_mfma_f32_32x32x2_f32 v[216:231], v124, v14, v[216:231]
	v_mfma_f32_32x32x2_f32 v[232:247], v124, v15, v[232:247]
	v_mfma_f32_32x32x2_f32 v[184:199], v125, v34, v[184:199]
	v_mfma_f32_32x32x2_f32 v[200:215], v125, v35, v[200:215]
	v_mfma_f32_32x32x2_f32 v[216:231], v125, v16, v[216:231]
	v_mfma_f32_32x32x2_f32 v[232:247], v125, v17, v[232:247]
	s_nop 18
	v_permlane32_swap_b32 v184, v216
	s_nop 18
	v_permlane32_swap_b32 v200, v232
	s_nop 16
	v_permlane32_swap_b32 v185, v217
; DI void ssm1_item(PREF p, int l, int item, unsigned char* ldsb) {
;     ...
;   for (int t = 0; t < 64; ++t) SSM_STEP(t)
	s_nop 16
	v_permlane32_swap_b32 v201, v233
	s_nop 14
	v_permlane32_swap_b32 v186, v218
	s_nop 14
	v_permlane32_swap_b32 v202, v234
	s_nop 12
	v_permlane32_swap_b32 v187, v219
	s_nop 12
	v_permlane32_swap_b32 v203, v235
	s_nop 10
	v_permlane32_swap_b32 v188, v220
	s_nop 10
	v_permlane32_swap_b32 v204, v236
	s_nop 8
	v_permlane32_swap_b32 v189, v221
	s_nop 8
	v_permlane32_swap_b32 v205, v237
	s_nop 6
	v_permlane32_swap_b32 v190, v222
	s_nop 6
	v_permlane32_swap_b32 v206, v238
	s_nop 4
	v_permlane32_swap_b32 v191, v223
	s_nop 4
	v_permlane32_swap_b32 v207, v239
	s_nop 2
	v_permlane32_swap_b32 v192, v224
	s_nop 2
	v_permlane32_swap_b32 v208, v240
	s_nop 0
	v_permlane32_swap_b32 v193, v225
	s_nop 0
	v_permlane32_swap_b32 v209, v241
	v_permlane32_swap_b32 v194, v226
	v_permlane32_swap_b32 v210, v242
	v_permlane32_swap_b32 v195, v227
	v_permlane32_swap_b32 v211, v243
	v_permlane32_swap_b32 v196, v228
	v_permlane32_swap_b32 v212, v244
	v_permlane32_swap_b32 v197, v229
	v_permlane32_swap_b32 v213, v245
	v_permlane32_swap_b32 v198, v230
	v_permlane32_swap_b32 v214, v246
	v_permlane32_swap_b32 v199, v231
	v_permlane32_swap_b32 v215, v247
	v_mul_f32_e32 v128, v23, v25
	v_mul_f32_e32 v129, v22, v25
	v_fma_f32 v130, v22, v24, -v128
	v_fma_f32 v131, v23, v24, v129
	v_add_f32_e32 v24, v130, v184
	v_add_f32_e32 v25, v131, v200
	v_mul_f32_e32 v128, v23, v25
	v_mul_f32_e32 v129, v22, v25
	v_fma_f32 v130, v22, v24, -v128
	v_fma_f32 v131, v23, v24, v129
	v_add_f32_e32 v24, v130, v185
	v_add_f32_e32 v25, v131, v201
	v_mul_f32_e32 v128, v23, v25
	v_mul_f32_e32 v129, v22, v25
	v_fma_f32 v130, v22, v24, -v128
	v_fma_f32 v131, v23, v24, v129
	v_add_f32_e32 v24, v130, v186
	v_add_f32_e32 v25, v131, v202
	v_mul_f32_e32 v128, v23, v25
	v_mul_f32_e32 v129, v22, v25
	v_fma_f32 v130, v22, v24, -v128
	v_fma_f32 v131, v23, v24, v129
	v_add_f32_e32 v24, v130, v187
	v_add_f32_e32 v25, v131, v203
	v_mul_f32_e32 v128, v23, v25
	v_mul_f32_e32 v129, v22, v25
	v_fma_f32 v130, v22, v24, -v128
	v_fma_f32 v131, v23, v24, v129
	v_add_f32_e32 v24, v130, v188
	v_add_f32_e32 v25, v131, v204
	v_mul_f32_e32 v128, v23, v25
	v_mul_f32_e32 v129, v22, v25
	v_fma_f32 v130, v22, v24, -v128
	v_fma_f32 v131, v23, v24, v129
	v_add_f32_e32 v24, v130, v189
	v_add_f32_e32 v25, v131, v205
	v_mul_f32_e32 v128, v23, v25
	v_mul_f32_e32 v129, v22, v25
	v_fma_f32 v130, v22, v24, -v128
	v_fma_f32 v131, v23, v24, v129
	v_add_f32_e32 v24, v130, v190
	v_add_f32_e32 v25, v131, v206
	v_mul_f32_e32 v128, v23, v25
	v_mul_f32_e32 v129, v22, v25
	v_fma_f32 v130, v22, v24, -v128
	v_fma_f32 v131, v23, v24, v129
	v_add_f32_e32 v24, v130, v191
	v_add_f32_e32 v25, v131, v207
	v_mul_f32_e32 v128, v23, v25
	v_mul_f32_e32 v129, v22, v25
	v_fma_f32 v130, v22, v24, -v128
	v_fma_f32 v131, v23, v24, v129
	v_add_f32_e32 v24, v130, v192
	v_add_f32_e32 v25, v131, v208
	v_mul_f32_e32 v128, v23, v25
	v_mul_f32_e32 v129, v22, v25
	v_fma_f32 v130, v22, v24, -v128
	v_fma_f32 v131, v23, v24, v129
	v_add_f32_e32 v24, v130, v193
	v_add_f32_e32 v25, v131, v209
	v_mul_f32_e32 v128, v23, v25
	v_mul_f32_e32 v129, v22, v25
	v_fma_f32 v130, v22, v24, -v128
	v_fma_f32 v131, v23, v24, v129
	v_add_f32_e32 v24, v130, v194
	v_add_f32_e32 v25, v131, v210
	v_mul_f32_e32 v128, v23, v25
	v_mul_f32_e32 v129, v22, v25
	v_fma_f32 v130, v22, v24, -v128
	v_fma_f32 v131, v23, v24, v129
	v_add_f32_e32 v24, v130, v195
	v_add_f32_e32 v25, v131, v211
	v_mul_f32_e32 v128, v23, v25
	v_mul_f32_e32 v129, v22, v25
	v_fma_f32 v130, v22, v24, -v128
	v_fma_f32 v131, v23, v24, v129
	v_add_f32_e32 v24, v130, v196
	v_add_f32_e32 v25, v131, v212
	v_mul_f32_e32 v128, v23, v25
	v_mul_f32_e32 v129, v22, v25
	v_fma_f32 v130, v22, v24, -v128
	v_fma_f32 v131, v23, v24, v129
	v_add_f32_e32 v24, v130, v197
	v_add_f32_e32 v25, v131, v213
	v_mul_f32_e32 v128, v23, v25
	v_mul_f32_e32 v129, v22, v25
; DI void ssm1_item(PREF p, int l, int item, unsigned char* ldsb) {
;     ...
;   for (int t = 0; t < 64; ++t) SSM_STEP(t)
;   ((float2*)p.hend)[((size_t)(b * 16 + g) * 64 + c) * 64 + lane] = make_float2(hr, hi);
	v_fma_f32 v130, v22, v24, -v128
	v_fma_f32 v131, v23, v24, v129
	v_add_f32_e32 v24, v130, v198
	v_add_f32_e32 v25, v131, v214
	v_mul_f32_e32 v128, v23, v25
	v_mul_f32_e32 v129, v22, v25
	v_fma_f32 v130, v22, v24, -v128
	v_fma_f32 v131, v23, v24, v129
	v_add_f32_e32 v24, v130, v199
	v_add_f32_e32 v25, v131, v215
	v_mul_f32_e32 v128, v23, v25
	v_mul_f32_e32 v129, v22, v25
	v_fma_f32 v130, v22, v24, -v128
	v_fma_f32 v131, v23, v24, v129
	v_add_f32_e32 v24, v130, v216
	v_add_f32_e32 v25, v131, v232
	v_mul_f32_e32 v128, v23, v25
	v_mul_f32_e32 v129, v22, v25
	v_fma_f32 v130, v22, v24, -v128
	v_fma_f32 v131, v23, v24, v129
	v_add_f32_e32 v24, v130, v217
	v_add_f32_e32 v25, v131, v233
	v_mul_f32_e32 v128, v23, v25
	v_mul_f32_e32 v129, v22, v25
	v_fma_f32 v130, v22, v24, -v128
	v_fma_f32 v131, v23, v24, v129
	v_add_f32_e32 v24, v130, v218
	v_add_f32_e32 v25, v131, v234
	v_mul_f32_e32 v128, v23, v25
	v_mul_f32_e32 v129, v22, v25
	v_fma_f32 v130, v22, v24, -v128
	v_fma_f32 v131, v23, v24, v129
	v_add_f32_e32 v24, v130, v219
	v_add_f32_e32 v25, v131, v235
	v_mul_f32_e32 v128, v23, v25
	v_mul_f32_e32 v129, v22, v25
	v_fma_f32 v130, v22, v24, -v128
	v_fma_f32 v131, v23, v24, v129
	v_add_f32_e32 v24, v130, v220
	v_add_f32_e32 v25, v131, v236
	v_mul_f32_e32 v128, v23, v25
	v_mul_f32_e32 v129, v22, v25
	v_fma_f32 v130, v22, v24, -v128
	v_fma_f32 v131, v23, v24, v129
	v_add_f32_e32 v24, v130, v221
	v_add_f32_e32 v25, v131, v237
	v_mul_f32_e32 v128, v23, v25
	v_mul_f32_e32 v129, v22, v25
	v_fma_f32 v130, v22, v24, -v128
	v_fma_f32 v131, v23, v24, v129
	v_add_f32_e32 v24, v130, v222
	v_add_f32_e32 v25, v131, v238
	v_mul_f32_e32 v128, v23, v25
	v_mul_f32_e32 v129, v22, v25
	v_fma_f32 v130, v22, v24, -v128
	v_fma_f32 v131, v23, v24, v129
	v_add_f32_e32 v24, v130, v223
	v_add_f32_e32 v25, v131, v239
	v_mul_f32_e32 v128, v23, v25
	v_mul_f32_e32 v129, v22, v25
	v_fma_f32 v130, v22, v24, -v128
	v_fma_f32 v131, v23, v24, v129
	v_add_f32_e32 v24, v130, v224
	v_add_f32_e32 v25, v131, v240
	v_mul_f32_e32 v128, v23, v25
	v_mul_f32_e32 v129, v22, v25
	v_fma_f32 v130, v22, v24, -v128
	v_fma_f32 v131, v23, v24, v129
	v_add_f32_e32 v24, v130, v225
	v_add_f32_e32 v25, v131, v241
	v_mul_f32_e32 v128, v23, v25
	v_mul_f32_e32 v129, v22, v25
	v_fma_f32 v130, v22, v24, -v128
	v_fma_f32 v131, v23, v24, v129
	v_add_f32_e32 v24, v130, v226
	v_add_f32_e32 v25, v131, v242
	v_mul_f32_e32 v128, v23, v25
	v_mul_f32_e32 v129, v22, v25
	v_fma_f32 v130, v22, v24, -v128
	v_fma_f32 v131, v23, v24, v129
	v_add_f32_e32 v24, v130, v227
	v_add_f32_e32 v25, v131, v243
	v_mul_f32_e32 v128, v23, v25
	v_mul_f32_e32 v129, v22, v25
	v_fma_f32 v130, v22, v24, -v128
	v_fma_f32 v131, v23, v24, v129
	v_add_f32_e32 v24, v130, v228
	v_add_f32_e32 v25, v131, v244
	v_mul_f32_e32 v128, v23, v25
	v_mul_f32_e32 v129, v22, v25
	v_fma_f32 v130, v22, v24, -v128
	v_fma_f32 v131, v23, v24, v129
	v_add_f32_e32 v24, v130, v229
	v_add_f32_e32 v25, v131, v245
	v_mul_f32_e32 v128, v23, v25
	v_mul_f32_e32 v129, v22, v25
	v_fma_f32 v130, v22, v24, -v128
	v_fma_f32 v131, v23, v24, v129
	v_add_f32_e32 v24, v130, v230
	v_add_f32_e32 v25, v131, v246
	v_mul_f32_e32 v128, v23, v25
	v_mul_f32_e32 v129, v22, v25
	v_fma_f32 v130, v22, v24, -v128
	v_fma_f32 v131, v23, v24, v129
	v_add_f32_e32 v24, v130, v231
	v_add_f32_e32 v25, v131, v247
	v_readlane_b32 s18, v254, 46
	v_readlane_b32 s19, v254, 47
	s_load_dwordx2 s[0:1], s[18:19], 0x188
	v_lshl_add_u32 v2, s14, 4, v41
	v_ashrrev_i32_e32 v3, 31, v2
	v_lshlrev_b64 v[2:3], 15, v[2:3]
	s_lshl_b32 s52, s15, 3
	s_waitcnt lgkmcnt(0)
	v_lshl_add_u64 v[2:3], s[0:1], 0, v[2:3]
	v_lshl_add_u64 v[2:3], v[2:3], 0, s[52:53]
	v_lshlrev_b32_e32 v0, 3, v0
	s_add_i32 s12, s12, s71
	v_lshl_add_u64 v[2:3], v[2:3], 0, v[0:1]
	s_cmpk_gt_i32 s12, 0x7ff
	global_store_dwordx2 v[2:3], v[24:25], off
	s_cbranch_scc0 .LBB0_422
